# P4/P9 sample-row GEMM: operand loads re-mapped so that adjacent lanes read contiguous bytes (16 rows x 64 B per instruction), fragments moved to the MFMA lane layout with ds_bpermute; double-buffered
# speedup vs baseline: 1.0174x; 1.0051x over previous
.LBB0_896:
	s_or_b64 exec, exec, s[38:39]
	s_lshl_b32 s19, s19, 6
	v_or_b32_e32 v4, s19, v17
	v_ashrrev_i32_e32 v5, 31, v4
	v_add_u32_e32 v2, s22, v50
	v_lshlrev_b64 v[4:5], 11, v[4:5]
	v_lshl_add_u64 v[24:25], v[12:13], 0, v[4:5]
	v_ashrrev_i32_e32 v3, 31, v2
	v_lshlrev_b64 v[2:3], 11, v[2:3]
	v_lshl_add_u64 v[26:27], v[10:11], 0, v[2:3]
	v_and_b32_e32 v2, 63, v204
	v_lshrrev_b32_e32 v3, 2, v2
	v_and_b32_e32 v4, 15, v2
	v_lshlrev_b32_e32 v199, 2, v4
	v_lshrrev_b32_e32 v5, 4, v2
	v_add_u32_e32 v199, v199, v5
	v_lshlrev_b32_e32 v199, 2, v199
	v_sub_u32_e32 v3, v3, v4
	v_lshlrev_b32_e32 v3, 11, v3
	v_and_b32_e32 v4, 3, v2
	v_lshlrev_b32_e32 v4, 4, v4
	v_and_b32_e32 v5, 48, v2
	v_sub_u32_e32 v4, v4, v5
	v_add_u32_e32 v2, v3, v4
	v_ashrrev_i32_e32 v3, 31, v2
	v_lshl_add_u64 v[24:25], v[24:25], 0, v[2:3]
	v_lshl_add_u64 v[26:27], v[26:27], 0, v[2:3]
	v_add_co_u32_e32 v18, vcc, 0x8000, v26
	s_nop 1
	v_addc_co_u32_e32 v19, vcc, 0, v27, vcc
	v_add_co_u32_e32 v20, vcc, 0x10000, v26
	s_nop 1
	v_addc_co_u32_e32 v21, vcc, 0, v27, vcc
	v_add_co_u32_e32 v22, vcc, 0x18000, v26
	s_nop 1
	v_addc_co_u32_e32 v23, vcc, 0, v27, vcc
	v_add_co_u32_e32 v28, vcc, s50, v24
	s_nop 1
	v_addc_co_u32_e32 v29, vcc, 0, v25, vcc
	v_add_co_u32_e32 v30, vcc, 0x10000, v24
	s_nop 1
	v_addc_co_u32_e32 v31, vcc, 0, v25, vcc
	v_add_co_u32_e32 v32, vcc, 0x18000, v24
	s_nop 1
	v_addc_co_u32_e32 v33, vcc, 0, v25, vcc
	global_load_dwordx4 v[116:119], v[24:25], off
	global_load_dwordx4 v[120:123], v[28:29], off
	global_load_dwordx4 v[124:127], v[30:31], off
	global_load_dwordx4 v[128:131], v[32:33], off
	global_load_dwordx4 v[132:135], v[26:27], off
	global_load_dwordx4 v[142:145], v[18:19], off
	global_load_dwordx4 v[146:149], v[20:21], off
	global_load_dwordx4 v[150:153], v[22:23], off
	global_load_dwordx4 v[154:157], v[24:25], off offset:64
	global_load_dwordx4 v[158:161], v[28:29], off offset:64
	global_load_dwordx4 v[162:165], v[30:31], off offset:64
	global_load_dwordx4 v[166:169], v[32:33], off offset:64
	global_load_dwordx4 v[170:173], v[26:27], off offset:64
	global_load_dwordx4 v[186:189], v[18:19], off offset:64
	global_load_dwordx4 v[190:193], v[20:21], off offset:64
	global_load_dwordx4 v[194:197], v[22:23], off offset:64
	s_waitcnt vmcnt(8)
	s_and_saveexec_b64 s[38:39], s[0:1]
	v_ffbh_u32_e32 v140, v137
	v_min_u32_e32 v140, 32, v140
	v_lshlrev_b64 v[136:137], v140, v[136:137]
	v_min_u32_e32 v136, 1, v136
	v_or_b32_e32 v136, v137, v136
	v_cvt_f32_u32_e32 v136, v136
	v_sub_u32_e32 v137, 32, v140
	v_ldexp_f32 v136, v136, v137
	v_fmamk_f32 v136, v136, 0x30800000, v207
	v_mul_f32_e32 v137, 0x4b800000, v136
	v_cmp_gt_f32_e32 vcc, s16, v136
	s_nop 1
	v_cndmask_b32_e32 v136, v136, v137, vcc
	v_rsq_f32_e32 v136, v136
	s_nop 0
	v_mul_f32_e32 v137, 0x45800000, v136
	v_cndmask_b32_e32 v16, v136, v137, vcc
	s_or_b64 exec, exec, s[38:39]
	s_and_saveexec_b64 s[38:39], s[42:43]
	v_ffbh_u32_e32 v140, v139
	v_min_u32_e32 v140, 32, v140
	v_lshlrev_b64 v[138:139], v140, v[138:139]
	v_min_u32_e32 v138, 1, v138
	v_or_b32_e32 v138, v139, v138
	v_cvt_f32_u32_e32 v138, v138
	v_sub_u32_e32 v139, 32, v140
	v_ldexp_f32 v138, v138, v139
	v_fmamk_f32 v138, v138, 0x30800000, v207
	v_mul_f32_e32 v139, 0x4b800000, v138
	v_cmp_gt_f32_e32 vcc, s16, v138
	s_nop 1
	v_cndmask_b32_e32 v138, v138, v139, vcc
	v_rsq_f32_e32 v138, v138
	s_nop 0
	v_mul_f32_e32 v139, 0x45800000, v138
	v_cndmask_b32_e32 v0, v138, v139, vcc
	s_or_b64 exec, exec, s[38:39]
	ds_bpermute_b32 v116, v199, v116
	ds_bpermute_b32 v117, v199, v117
	ds_bpermute_b32 v118, v199, v118
	ds_bpermute_b32 v119, v199, v119
	ds_bpermute_b32 v120, v199, v120
	ds_bpermute_b32 v121, v199, v121
	ds_bpermute_b32 v122, v199, v122
	ds_bpermute_b32 v123, v199, v123
	ds_bpermute_b32 v124, v199, v124
	ds_bpermute_b32 v125, v199, v125
	ds_bpermute_b32 v126, v199, v126
	ds_bpermute_b32 v127, v199, v127
	ds_bpermute_b32 v128, v199, v128
	ds_bpermute_b32 v129, v199, v129
	ds_bpermute_b32 v130, v199, v130
	ds_bpermute_b32 v131, v199, v131
	s_waitcnt lgkmcnt(0)
	ds_bpermute_b32 v132, v199, v132
	ds_bpermute_b32 v133, v199, v133
	ds_bpermute_b32 v134, v199, v134
	ds_bpermute_b32 v135, v199, v135
	ds_bpermute_b32 v142, v199, v142
	ds_bpermute_b32 v143, v199, v143
	ds_bpermute_b32 v144, v199, v144
	ds_bpermute_b32 v145, v199, v145
	ds_bpermute_b32 v146, v199, v146
	ds_bpermute_b32 v147, v199, v147
	ds_bpermute_b32 v148, v199, v148
	ds_bpermute_b32 v149, v199, v149
	ds_bpermute_b32 v150, v199, v150
	ds_bpermute_b32 v151, v199, v151
	ds_bpermute_b32 v152, v199, v152
	ds_bpermute_b32 v153, v199, v153
	s_waitcnt lgkmcnt(0)
	v_mfma_f32_16x16x32_bf16 v[52:55], v[116:119], v[132:135], 0
	v_mfma_f32_16x16x32_bf16 v[56:59], v[120:123], v[132:135], 0
	v_mfma_f32_16x16x32_bf16 v[60:63], v[124:127], v[132:135], 0
	v_mfma_f32_16x16x32_bf16 v[64:67], v[128:131], v[132:135], 0
	v_mfma_f32_16x16x32_bf16 v[68:71], v[116:119], v[142:145], 0
	v_mfma_f32_16x16x32_bf16 v[72:75], v[120:123], v[142:145], 0
	v_mfma_f32_16x16x32_bf16 v[76:79], v[124:127], v[142:145], 0
	v_mfma_f32_16x16x32_bf16 v[80:83], v[128:131], v[142:145], 0
	v_mfma_f32_16x16x32_bf16 v[84:87], v[116:119], v[146:149], 0
	v_mfma_f32_16x16x32_bf16 v[88:91], v[120:123], v[146:149], 0
	v_mfma_f32_16x16x32_bf16 v[92:95], v[124:127], v[146:149], 0
	v_mfma_f32_16x16x32_bf16 v[96:99], v[128:131], v[146:149], 0
	v_mfma_f32_16x16x32_bf16 v[100:103], v[116:119], v[150:153], 0
	v_mfma_f32_16x16x32_bf16 v[104:107], v[120:123], v[150:153], 0
	v_mfma_f32_16x16x32_bf16 v[108:111], v[124:127], v[150:153], 0
	v_mfma_f32_16x16x32_bf16 v[112:115], v[128:131], v[150:153], 0
	global_load_dwordx4 v[116:119], v[24:25], off offset:128
	global_load_dwordx4 v[120:123], v[28:29], off offset:128
	global_load_dwordx4 v[124:127], v[30:31], off offset:128
	global_load_dwordx4 v[128:131], v[32:33], off offset:128
	global_load_dwordx4 v[132:135], v[26:27], off offset:128
	global_load_dwordx4 v[142:145], v[18:19], off offset:128
	global_load_dwordx4 v[146:149], v[20:21], off offset:128
	global_load_dwordx4 v[150:153], v[22:23], off offset:128
	s_waitcnt vmcnt(8)
	ds_bpermute_b32 v154, v199, v154
	ds_bpermute_b32 v155, v199, v155
	ds_bpermute_b32 v156, v199, v156
	ds_bpermute_b32 v157, v199, v157
	ds_bpermute_b32 v158, v199, v158
	ds_bpermute_b32 v159, v199, v159
	ds_bpermute_b32 v160, v199, v160
	ds_bpermute_b32 v161, v199, v161
	ds_bpermute_b32 v162, v199, v162
	ds_bpermute_b32 v163, v199, v163
	ds_bpermute_b32 v164, v199, v164
	ds_bpermute_b32 v165, v199, v165
	ds_bpermute_b32 v166, v199, v166
	ds_bpermute_b32 v167, v199, v167
	ds_bpermute_b32 v168, v199, v168
	ds_bpermute_b32 v169, v199, v169
	s_waitcnt lgkmcnt(0)
	ds_bpermute_b32 v170, v199, v170
	ds_bpermute_b32 v171, v199, v171
	ds_bpermute_b32 v172, v199, v172
	ds_bpermute_b32 v173, v199, v173
	ds_bpermute_b32 v186, v199, v186
	ds_bpermute_b32 v187, v199, v187
	ds_bpermute_b32 v188, v199, v188
	ds_bpermute_b32 v189, v199, v189
	ds_bpermute_b32 v190, v199, v190
	ds_bpermute_b32 v191, v199, v191
	ds_bpermute_b32 v192, v199, v192
	ds_bpermute_b32 v193, v199, v193
	ds_bpermute_b32 v194, v199, v194
	ds_bpermute_b32 v195, v199, v195
	ds_bpermute_b32 v196, v199, v196
	ds_bpermute_b32 v197, v199, v197
	s_waitcnt lgkmcnt(0)
	v_mfma_f32_16x16x32_bf16 v[52:55], v[154:157], v[170:173], v[52:55]
	v_mfma_f32_16x16x32_bf16 v[56:59], v[158:161], v[170:173], v[56:59]
	v_mfma_f32_16x16x32_bf16 v[60:63], v[162:165], v[170:173], v[60:63]
	v_mfma_f32_16x16x32_bf16 v[64:67], v[166:169], v[170:173], v[64:67]
	v_mfma_f32_16x16x32_bf16 v[68:71], v[154:157], v[186:189], v[68:71]
	v_mfma_f32_16x16x32_bf16 v[72:75], v[158:161], v[186:189], v[72:75]
	v_mfma_f32_16x16x32_bf16 v[76:79], v[162:165], v[186:189], v[76:79]
	v_mfma_f32_16x16x32_bf16 v[80:83], v[166:169], v[186:189], v[80:83]
	v_mfma_f32_16x16x32_bf16 v[84:87], v[154:157], v[190:193], v[84:87]
	v_mfma_f32_16x16x32_bf16 v[88:91], v[158:161], v[190:193], v[88:91]
	v_mfma_f32_16x16x32_bf16 v[92:95], v[162:165], v[190:193], v[92:95]
	v_mfma_f32_16x16x32_bf16 v[96:99], v[166:169], v[190:193], v[96:99]
	v_mfma_f32_16x16x32_bf16 v[100:103], v[154:157], v[194:197], v[100:103]
	v_mfma_f32_16x16x32_bf16 v[104:107], v[158:161], v[194:197], v[104:107]
	v_mfma_f32_16x16x32_bf16 v[108:111], v[162:165], v[194:197], v[108:111]
	v_mfma_f32_16x16x32_bf16 v[112:115], v[166:169], v[194:197], v[112:115]
	global_load_dwordx4 v[154:157], v[24:25], off offset:192
	global_load_dwordx4 v[158:161], v[28:29], off offset:192
	global_load_dwordx4 v[162:165], v[30:31], off offset:192
	global_load_dwordx4 v[166:169], v[32:33], off offset:192
	global_load_dwordx4 v[170:173], v[26:27], off offset:192
	global_load_dwordx4 v[186:189], v[18:19], off offset:192
	global_load_dwordx4 v[190:193], v[20:21], off offset:192
	global_load_dwordx4 v[194:197], v[22:23], off offset:192
	s_waitcnt vmcnt(8)
	ds_bpermute_b32 v116, v199, v116
	ds_bpermute_b32 v117, v199, v117
	ds_bpermute_b32 v118, v199, v118
	ds_bpermute_b32 v119, v199, v119
	ds_bpermute_b32 v120, v199, v120
	ds_bpermute_b32 v121, v199, v121
	ds_bpermute_b32 v122, v199, v122
	ds_bpermute_b32 v123, v199, v123
	ds_bpermute_b32 v124, v199, v124
	ds_bpermute_b32 v125, v199, v125
	ds_bpermute_b32 v126, v199, v126
	ds_bpermute_b32 v127, v199, v127
	ds_bpermute_b32 v128, v199, v128
	ds_bpermute_b32 v129, v199, v129
	ds_bpermute_b32 v130, v199, v130
	ds_bpermute_b32 v131, v199, v131
	s_waitcnt lgkmcnt(0)
	ds_bpermute_b32 v132, v199, v132
	ds_bpermute_b32 v133, v199, v133
	ds_bpermute_b32 v134, v199, v134
	ds_bpermute_b32 v135, v199, v135
	ds_bpermute_b32 v142, v199, v142
	ds_bpermute_b32 v143, v199, v143
	ds_bpermute_b32 v144, v199, v144
	ds_bpermute_b32 v145, v199, v145
	ds_bpermute_b32 v146, v199, v146
	ds_bpermute_b32 v147, v199, v147
	ds_bpermute_b32 v148, v199, v148
	ds_bpermute_b32 v149, v199, v149
	ds_bpermute_b32 v150, v199, v150
	ds_bpermute_b32 v151, v199, v151
	ds_bpermute_b32 v152, v199, v152
	ds_bpermute_b32 v153, v199, v153
	s_waitcnt lgkmcnt(0)
	v_mfma_f32_16x16x32_bf16 v[52:55], v[116:119], v[132:135], v[52:55]
	v_mfma_f32_16x16x32_bf16 v[56:59], v[120:123], v[132:135], v[56:59]
	v_mfma_f32_16x16x32_bf16 v[60:63], v[124:127], v[132:135], v[60:63]
	v_mfma_f32_16x16x32_bf16 v[64:67], v[128:131], v[132:135], v[64:67]
	v_mfma_f32_16x16x32_bf16 v[68:71], v[116:119], v[142:145], v[68:71]
	v_mfma_f32_16x16x32_bf16 v[72:75], v[120:123], v[142:145], v[72:75]
	v_mfma_f32_16x16x32_bf16 v[76:79], v[124:127], v[142:145], v[76:79]
	v_mfma_f32_16x16x32_bf16 v[80:83], v[128:131], v[142:145], v[80:83]
	v_mfma_f32_16x16x32_bf16 v[84:87], v[116:119], v[146:149], v[84:87]
	v_mfma_f32_16x16x32_bf16 v[88:91], v[120:123], v[146:149], v[88:91]
	v_mfma_f32_16x16x32_bf16 v[92:95], v[124:127], v[146:149], v[92:95]
	v_mfma_f32_16x16x32_bf16 v[96:99], v[128:131], v[146:149], v[96:99]
	v_mfma_f32_16x16x32_bf16 v[100:103], v[116:119], v[150:153], v[100:103]
	v_mfma_f32_16x16x32_bf16 v[104:107], v[120:123], v[150:153], v[104:107]
	v_mfma_f32_16x16x32_bf16 v[108:111], v[124:127], v[150:153], v[108:111]
	v_mfma_f32_16x16x32_bf16 v[112:115], v[128:131], v[150:153], v[112:115]
	s_waitcnt vmcnt(0)
	ds_bpermute_b32 v154, v199, v154
	ds_bpermute_b32 v155, v199, v155
	ds_bpermute_b32 v156, v199, v156
	ds_bpermute_b32 v157, v199, v157
	ds_bpermute_b32 v158, v199, v158
	ds_bpermute_b32 v159, v199, v159
	ds_bpermute_b32 v160, v199, v160
	ds_bpermute_b32 v161, v199, v161
	ds_bpermute_b32 v162, v199, v162
	ds_bpermute_b32 v163, v199, v163
	ds_bpermute_b32 v164, v199, v164
	ds_bpermute_b32 v165, v199, v165
	ds_bpermute_b32 v166, v199, v166
	ds_bpermute_b32 v167, v199, v167
	ds_bpermute_b32 v168, v199, v168
	ds_bpermute_b32 v169, v199, v169
	s_waitcnt lgkmcnt(0)
	ds_bpermute_b32 v170, v199, v170
	ds_bpermute_b32 v171, v199, v171
	ds_bpermute_b32 v172, v199, v172
	ds_bpermute_b32 v173, v199, v173
	ds_bpermute_b32 v186, v199, v186
	ds_bpermute_b32 v187, v199, v187
	ds_bpermute_b32 v188, v199, v188
	ds_bpermute_b32 v189, v199, v189
	ds_bpermute_b32 v190, v199, v190
	ds_bpermute_b32 v191, v199, v191
	ds_bpermute_b32 v192, v199, v192
	ds_bpermute_b32 v193, v199, v193
	ds_bpermute_b32 v194, v199, v194
	ds_bpermute_b32 v195, v199, v195
	ds_bpermute_b32 v196, v199, v196
	ds_bpermute_b32 v197, v199, v197
	s_waitcnt lgkmcnt(0)
	v_mfma_f32_16x16x32_bf16 v[52:55], v[154:157], v[170:173], v[52:55]
	v_mfma_f32_16x16x32_bf16 v[56:59], v[158:161], v[170:173], v[56:59]
	v_mfma_f32_16x16x32_bf16 v[60:63], v[162:165], v[170:173], v[60:63]
	v_mfma_f32_16x16x32_bf16 v[64:67], v[166:169], v[170:173], v[64:67]
	v_mfma_f32_16x16x32_bf16 v[68:71], v[154:157], v[186:189], v[68:71]
	v_mfma_f32_16x16x32_bf16 v[72:75], v[158:161], v[186:189], v[72:75]
	v_mfma_f32_16x16x32_bf16 v[76:79], v[162:165], v[186:189], v[76:79]
	v_mfma_f32_16x16x32_bf16 v[80:83], v[166:169], v[186:189], v[80:83]
	v_mfma_f32_16x16x32_bf16 v[84:87], v[154:157], v[190:193], v[84:87]
	v_mfma_f32_16x16x32_bf16 v[88:91], v[158:161], v[190:193], v[88:91]
	v_mfma_f32_16x16x32_bf16 v[92:95], v[162:165], v[190:193], v[92:95]
	v_mfma_f32_16x16x32_bf16 v[96:99], v[166:169], v[190:193], v[96:99]
	v_mfma_f32_16x16x32_bf16 v[100:103], v[154:157], v[194:197], v[100:103]
	v_mfma_f32_16x16x32_bf16 v[104:107], v[158:161], v[194:197], v[104:107]
	v_mfma_f32_16x16x32_bf16 v[108:111], v[162:165], v[194:197], v[108:111]
	v_mfma_f32_16x16x32_bf16 v[112:115], v[166:169], v[194:197], v[112:115]
	v_add_u32_e32 v22, s20, v34
	s_nop 7
	ds_write_b128 v22, v[52:55]
	ds_write_b128 v22, v[56:59] offset:1024
	ds_write_b128 v22, v[60:63] offset:2048
	ds_write_b128 v22, v[64:67] offset:3072
	ds_write_b128 v22, v[68:71] offset:4096
	ds_write_b128 v22, v[72:75] offset:5120
	ds_write_b128 v22, v[76:79] offset:6144
	ds_write_b128 v22, v[80:83] offset:7168
	ds_write_b128 v22, v[84:87] offset:8192
	ds_write_b128 v22, v[88:91] offset:9216
	ds_write_b128 v22, v[92:95] offset:10240
	ds_write_b128 v22, v[96:99] offset:11264
	ds_write_b128 v22, v[100:103] offset:12288
	ds_write_b128 v22, v[104:107] offset:13312
	ds_write_b128 v22, v[108:111] offset:14336
	ds_write_b128 v22, v[112:115] offset:15360
	s_waitcnt lgkmcnt(0)
	s_barrier
	s_and_saveexec_b64 s[38:39], s[0:1]
	s_cbranch_execz .LBB0_891
	ds_read_b128 v[4:7], v36
	ds_read_b128 v[18:21], v37 offset:16384
	v_or_b32_e32 v2, s19, v35
	v_lshlrev_b64 v[14:15], 13, v[14:15]
	v_lshl_add_u64 v[14:15], s[68:69], 0, v[14:15]
	s_waitcnt lgkmcnt(0)
	v_pk_add_f32 v[8:9], v[6:7], v[20:21]
	v_pk_add_f32 v[18:19], v[4:5], v[18:19]
	ds_read_b128 v[4:7], v37 offset:32768
	s_waitcnt lgkmcnt(0)
	v_pk_add_f32 v[8:9], v[8:9], v[6:7]
	v_pk_add_f32 v[18:19], v[18:19], v[4:5]
	ds_read_b128 v[4:7], v37 offset:49152
	s_waitcnt lgkmcnt(0)
	v_pk_add_f32 v[8:9], v[8:9], v[6:7]
	v_pk_add_f32 v[18:19], v[18:19], v[4:5]
	ds_read_b128 v[4:7], v38
	s_waitcnt lgkmcnt(0)
	v_pk_add_f32 v[8:9], v[8:9], v[6:7]
	v_pk_add_f32 v[18:19], v[18:19], v[4:5]
	ds_read_b128 v[4:7], v39
	s_waitcnt lgkmcnt(0)
	v_pk_add_f32 v[8:9], v[8:9], v[6:7]
	v_pk_add_f32 v[18:19], v[18:19], v[4:5]
	ds_read_b128 v[4:7], v40
	s_waitcnt lgkmcnt(0)
	v_pk_add_f32 v[8:9], v[8:9], v[6:7]
	v_pk_add_f32 v[18:19], v[18:19], v[4:5]
	ds_read_b128 v[4:7], v41
	s_waitcnt lgkmcnt(0)
	v_pk_add_f32 v[6:7], v[8:9], v[6:7]
	v_pk_add_f32 v[4:5], v[18:19], v[4:5]
	v_pk_mul_f32 v[6:7], v[16:17], v[6:7] op_sel_hi:[0,1]
	v_pk_mul_f32 v[4:5], v[16:17], v[4:5] op_sel_hi:[0,1]
	v_add_u32_e32 v8, v2, v42
	v_max_f32_e32 v5, 0, v5
	v_max_f32_e32 v4, 0, v4
	v_max_f32_e32 v7, 0, v7
	v_max_f32_e32 v6, 0, v6
	v_pk_mul_f32 v[6:7], v[6:7], v[6:7]
	v_pk_mul_f32 v[4:5], v[4:5], v[4:5]
	v_ashrrev_i32_e32 v9, 31, v8
	v_lshl_add_u64 v[8:9], v[8:9], 1, v[14:15]
	v_cvt_pk_bf16_f32 v4, v4, v5
	v_cvt_pk_bf16_f32 v5, v6, v7
	global_store_dwordx2 v[8:9], v[4:5], off
	s_and_b64 exec, exec, s[42:43]
	s_cbranch_execz .LBB0_891
	ds_read_b128 v[4:7], v36 offset:8192
	ds_read_b128 v[18:21], v43 offset:16384
	v_add_u32_e32 v2, v2, v48
	v_ashrrev_i32_e32 v3, 31, v2
	s_waitcnt lgkmcnt(0)
	v_pk_add_f32 v[8:9], v[6:7], v[20:21]
	v_pk_add_f32 v[14:15], v[4:5], v[18:19]
	ds_read_b128 v[4:7], v43 offset:32768
	s_waitcnt lgkmcnt(0)
	v_pk_add_f32 v[8:9], v[8:9], v[6:7]
	v_pk_add_f32 v[14:15], v[14:15], v[4:5]
	ds_read_b128 v[4:7], v43 offset:49152
	s_waitcnt lgkmcnt(0)
	v_pk_add_f32 v[8:9], v[8:9], v[6:7]
	v_pk_add_f32 v[14:15], v[14:15], v[4:5]
	ds_read_b128 v[4:7], v44
	s_waitcnt lgkmcnt(0)
	v_pk_add_f32 v[8:9], v[8:9], v[6:7]
	v_pk_add_f32 v[14:15], v[14:15], v[4:5]
	ds_read_b128 v[4:7], v45
	s_waitcnt lgkmcnt(0)
	v_pk_add_f32 v[8:9], v[8:9], v[6:7]
	v_pk_add_f32 v[14:15], v[14:15], v[4:5]
	ds_read_b128 v[4:7], v46
	s_waitcnt lgkmcnt(0)
	v_pk_add_f32 v[8:9], v[8:9], v[6:7]
	v_pk_add_f32 v[14:15], v[14:15], v[4:5]
	ds_read_b128 v[4:7], v47
	s_waitcnt lgkmcnt(0)
	v_pk_add_f32 v[6:7], v[8:9], v[6:7]
	v_pk_add_f32 v[4:5], v[14:15], v[4:5]
	v_add3_u32 v8, v51, v50, s22
	v_pk_mul_f32 v[6:7], v[0:1], v[6:7] op_sel_hi:[0,1]
	v_pk_mul_f32 v[4:5], v[0:1], v[4:5] op_sel_hi:[0,1]
	v_ashrrev_i32_e32 v9, 31, v8
	v_max_f32_e32 v5, 0, v5
	v_max_f32_e32 v4, 0, v4
	v_max_f32_e32 v7, 0, v7
	v_max_f32_e32 v6, 0, v6
	v_lshlrev_b64 v[8:9], 13, v[8:9]
	v_pk_mul_f32 v[6:7], v[6:7], v[6:7]
	v_pk_mul_f32 v[4:5], v[4:5], v[4:5]
	v_lshl_add_u64 v[8:9], s[68:69], 0, v[8:9]
	v_lshl_add_u64 v[2:3], v[2:3], 1, v[8:9]
	v_cvt_pk_bf16_f32 v4, v4, v5
	v_cvt_pk_bf16_f32 v5, v6, v7
	global_store_dwordx2 v[2:3], v[4:5], off
	s_branch .LBB0_891
